# EpiSplit: leading-half align barrier sunk below the 8 row-stat loads (dt path gets its own copy); otherwise identical to v27
# baseline (speedup 1.0000x reference)
; __device__ __forceinline__ unsigned cvt_pk_bf16(float lo, float hi) { f32x2_cv v = {lo, hi}; bf16x2_cv b = __builtin_convertvector(v, bf16x2_cv); return __builtin_bit_cast(unsigned, b); }
; __device__ __forceinline__ float row_rstd(const float* rsp, int row, int fq) {
;     const f32x4 v = *(const f32x4*)(rsp + (size_t)row * 16 + 4 * fq);
;     float s = (v[0] + v[1]) + (v[2] + v[3]); s += __shfl_xor(s, 16); s += __shfl_xor(s, 32);
;     return rsqrtf(s * (1.0f / 1024.0f) + RMS_EPS);
;     __device__ __forceinline__ void operator()(const f32x4 (&acc)[2][2][4][2], const Unit& u, int wr, int wc, int fr, int fq) const {
;     ...
;         const int t = u.pn / tiles_per_split; bf16_t* base = O + (size_t)t * split_stride; const int colt = (u.pn - t * tiles_per_split) * BM + wc * 32 + 8 * fq;
;         const float sc = (t == 0) ? scale0 : 1.0f;
; #pragma unroll
;         for (int ai = 0; ai < 2; ++ai)
; #pragma unroll
;             for (int m = 0; m < 4; ++m) {
;                 const int row = row0 + ai * HALF + m * 16; const float rs = row_rstd(rsp, row, fq) * sc;
;                 bf16_t* rowp = base + (size_t)row * ldc + colt;
; #pragma unroll
;                 for (int bj = 0; bj < 2; ++bj) {
;                     const f32x4 v0 = acc[ai][bj][m][0] * rs, v1 = acc[ai][bj][m][1] * rs;
;                     u32x4 w; w.x = cvt_pk_bf16(v0[0], v0[1]); w.y = cvt_pk_bf16(v0[2], v0[3]); w.z = cvt_pk_bf16(v1[0], v1[1]); w.w = cvt_pk_bf16(v1[2], v1[3]);
;                     *(u32x4*)(rowp + bj * HALF) = w;
.LBB0_333:
	v_lshl_add_u32 v144, s26, 8, v148
	s_cmp_lg_u32 s59, s51
	s_mov_b64 s[26:27], -1
	s_mov_b64 s[60:61], 0x200000
	s_mov_b64 s[62:63], s[80:81]
	s_cbranch_scc0 .Lsplit_dt_align
	v_mov_b32_e32 v145, 0
	v_lshlrev_b64 v[156:157], 6, v[144:145]
	v_lshl_add_u64 v[156:157], v[136:137], 0, v[156:157]
	v_add_co_u32_e32 v218, vcc, 0x2000, v156
	s_nop 1
	v_addc_co_u32_e32 v219, vcc, 0, v157, vcc
	global_load_dwordx4 v[172:175], v[156:157], off
	global_load_dwordx4 v[176:179], v[156:157], off offset:1024
	global_load_dwordx4 v[180:183], v[156:157], off offset:2048
	global_load_dwordx4 v[184:187], v[156:157], off offset:3072
	global_load_dwordx4 v[188:191], v[218:219], off
	global_load_dwordx4 v[192:195], v[218:219], off offset:1024
	global_load_dwordx4 v[196:199], v[218:219], off offset:2048
	global_load_dwordx4 v[214:217], v[218:219], off offset:3072
	s_abs_i32 s21, s59
	s_mul_hi_u32 s26, s21, s58
	s_mul_i32 s27, s26, s50
	s_sub_i32 s21, s21, s27
	s_ashr_i32 s19, s59, 31
	s_add_i32 s27, s26, 1
	s_sub_i32 s28, s21, s50
	s_cmp_ge_u32 s21, s50
	s_cselect_b32 s26, s27, s26
	s_cselect_b32 s21, s28, s21
	s_add_i32 s27, s26, 1
	s_cmp_ge_u32 s21, s50
	s_cselect_b32 s21, s27, s26
	s_xor_b32 s21, s21, s19
	s_sub_i32 s26, s21, s19
	s_ashr_i32 s27, s26, 31
	s_lshl_b64 s[28:29], s[26:27], s55
	s_lshl_b64 s[28:29], s[28:29], 1
	s_add_u32 s28, s0, s28
	s_addc_u32 s29, s1, s29
	s_lshl_b32 s19, s26, s56
	s_sub_i32 s19, s59, s19
	s_cmp_eq_u32 s26, 0
	s_cselect_b64 s[26:27], -1, 0
	s_and_b64 vcc, s[26:27], s[12:13]
	v_xor_b32_e32 v153, 16, v201
	v_xor_b32_e32 v154, 32, v201
	v_cndmask_b32_e32 v152, 1.0, v211, vcc
	v_lshl_or_b32 v146, s19, 8, v150
	s_mov_b64 s[26:27], 0
	v_lshlrev_b32_e32 v153, 2, v153
	v_lshlrev_b32_e32 v154, 2, v154
	v_ashrrev_i32_e32 v147, 31, v146
	v_lshl_add_u64 v[146:147], v[146:147], 1, s[28:29]
	v_mov_b32_e32 v225, 0
	s_and_b64 vcc, exec, s[14:15]
	s_cbranch_vccz .Lsplit_aligned
	s_barrier
.Lsplit_aligned:
	s_waitcnt vmcnt(0)
	v_add_f32_e32 v172, v172, v173
	v_add_f32_e32 v176, v176, v177
	v_add_f32_e32 v180, v180, v181
	v_add_f32_e32 v184, v184, v185
	v_add_f32_e32 v188, v188, v189
	v_add_f32_e32 v192, v192, v193
	v_add_f32_e32 v196, v196, v197
	v_add_f32_e32 v214, v214, v215
	v_add_f32_e32 v174, v174, v175
	v_add_f32_e32 v178, v178, v179
	v_add_f32_e32 v182, v182, v183
	v_add_f32_e32 v186, v186, v187
	v_add_f32_e32 v190, v190, v191
	v_add_f32_e32 v194, v194, v195
	v_add_f32_e32 v198, v198, v199
	v_add_f32_e32 v216, v216, v217
	v_add_f32_e32 v172, v172, v174
	v_add_f32_e32 v176, v176, v178
	v_add_f32_e32 v180, v180, v182
	v_add_f32_e32 v184, v184, v186
	v_add_f32_e32 v188, v188, v190
	v_add_f32_e32 v192, v192, v194
	v_add_f32_e32 v196, v196, v198
	v_add_f32_e32 v214, v214, v216
	ds_bpermute_b32 v173, v153, v172
	ds_bpermute_b32 v177, v153, v176
	ds_bpermute_b32 v181, v153, v180
	ds_bpermute_b32 v185, v153, v184
	ds_bpermute_b32 v189, v153, v188
	ds_bpermute_b32 v193, v153, v192
	ds_bpermute_b32 v197, v153, v196
	ds_bpermute_b32 v215, v153, v214
	s_waitcnt lgkmcnt(0)
	v_add_f32_e32 v172, v172, v173
	v_add_f32_e32 v176, v176, v177
	v_add_f32_e32 v180, v180, v181
	v_add_f32_e32 v184, v184, v185
	v_add_f32_e32 v188, v188, v189
	v_add_f32_e32 v192, v192, v193
	v_add_f32_e32 v196, v196, v197
	v_add_f32_e32 v214, v214, v215
	ds_bpermute_b32 v173, v154, v172
	ds_bpermute_b32 v177, v154, v176
	ds_bpermute_b32 v181, v154, v180
	ds_bpermute_b32 v185, v154, v184
	ds_bpermute_b32 v189, v154, v188
	ds_bpermute_b32 v193, v154, v192
	ds_bpermute_b32 v197, v154, v196
	ds_bpermute_b32 v215, v154, v214
	s_waitcnt lgkmcnt(0)
	v_add_f32_e32 v172, v172, v173
	v_add_f32_e32 v176, v176, v177
	v_add_f32_e32 v180, v180, v181
	v_add_f32_e32 v184, v184, v185
	v_add_f32_e32 v188, v188, v189
	v_add_f32_e32 v192, v192, v193
	v_add_f32_e32 v196, v196, v197
	v_add_f32_e32 v214, v214, v215
	v_fmamk_f32 v172, v172, 0x3a800000, v207
	v_fmamk_f32 v176, v176, 0x3a800000, v207
	v_fmamk_f32 v180, v180, 0x3a800000, v207
	v_fmamk_f32 v184, v184, 0x3a800000, v207
	v_fmamk_f32 v188, v188, 0x3a800000, v207
	v_fmamk_f32 v192, v192, 0x3a800000, v207
	v_fmamk_f32 v196, v196, 0x3a800000, v207
	v_fmamk_f32 v214, v214, 0x3a800000, v207
	v_rsq_f32_e32 v172, v172
	v_rsq_f32_e32 v176, v176
	v_rsq_f32_e32 v180, v180
	v_rsq_f32_e32 v184, v184
	v_rsq_f32_e32 v188, v188
	v_rsq_f32_e32 v192, v192
	v_rsq_f32_e32 v196, v196
	v_rsq_f32_e32 v214, v214
	v_mul_f32_e32 v172, v152, v172
	v_mul_f32_e32 v176, v152, v176
	v_mul_f32_e32 v180, v152, v180
	v_mul_f32_e32 v184, v152, v184
	v_mul_f32_e32 v188, v152, v188
	v_mul_f32_e32 v192, v152, v192
	v_mul_f32_e32 v196, v152, v196
	v_mul_f32_e32 v214, v152, v214
	v_mov_b32_e32 v224, v144
	v_lshlrev_b64 v[222:223], s57, v[224:225]
	v_lshl_add_u64 v[220:221], v[222:223], 1, v[146:147]
	v_pk_mul_f32 v[62:63], v[62:63], v[172:173] op_sel_hi:[1,0]
	v_pk_mul_f32 v[64:65], v[64:65], v[172:173] op_sel_hi:[1,0]
	v_pk_mul_f32 v[58:59], v[58:59], v[172:173] op_sel_hi:[1,0]
	v_pk_mul_f32 v[60:61], v[60:61], v[172:173] op_sel_hi:[1,0]
	v_pk_mul_f32 v[126:127], v[126:127], v[172:173] op_sel_hi:[1,0]
	v_pk_mul_f32 v[128:129], v[128:129], v[172:173] op_sel_hi:[1,0]
	v_pk_mul_f32 v[122:123], v[122:123], v[172:173] op_sel_hi:[1,0]
	v_pk_mul_f32 v[124:125], v[124:125], v[172:173] op_sel_hi:[1,0]
	v_cvt_pk_bf16_f32 v226, v62, v63
	v_cvt_pk_bf16_f32 v227, v64, v65
	v_cvt_pk_bf16_f32 v228, v58, v59
	v_cvt_pk_bf16_f32 v229, v60, v61
	v_cvt_pk_bf16_f32 v230, v126, v127
	v_cvt_pk_bf16_f32 v231, v128, v129
	v_cvt_pk_bf16_f32 v232, v122, v123
	v_cvt_pk_bf16_f32 v233, v124, v125
	global_store_dwordx4 v[220:221], v[226:229], off
	global_store_dwordx4 v[220:221], v[230:233], off offset:256
; __device__ __forceinline__ unsigned cvt_pk_bf16(float lo, float hi) { f32x2_cv v = {lo, hi}; bf16x2_cv b = __builtin_convertvector(v, bf16x2_cv); return __builtin_bit_cast(unsigned, b); }
;     __device__ __forceinline__ void operator()(const f32x4 (&acc)[2][2][4][2], const Unit& u, int wr, int wc, int fr, int fq) const {
;     ...
; #pragma unroll
;         for (int ai = 0; ai < 2; ++ai)
; #pragma unroll
;             for (int m = 0; m < 4; ++m) {
;                 const int row = row0 + ai * HALF + m * 16; const float rs = row_rstd(rsp, row, fq) * sc;
;                 bf16_t* rowp = base + (size_t)row * ldc + colt;
; #pragma unroll
;                 for (int bj = 0; bj < 2; ++bj) {
;                     const f32x4 v0 = acc[ai][bj][m][0] * rs, v1 = acc[ai][bj][m][1] * rs;
;                     u32x4 w; w.x = cvt_pk_bf16(v0[0], v0[1]); w.y = cvt_pk_bf16(v0[2], v0[3]); w.z = cvt_pk_bf16(v1[0], v1[1]); w.w = cvt_pk_bf16(v1[2], v1[3]);
;                     *(u32x4*)(rowp + bj * HALF) = w;
;                 }
;             }
	v_add_u32_e32 v224, 0x10, v144
	v_lshlrev_b64 v[222:223], s57, v[224:225]
	v_lshl_add_u64 v[220:221], v[222:223], 1, v[146:147]
	v_pk_mul_f32 v[54:55], v[54:55], v[176:177] op_sel_hi:[1,0]
	v_pk_mul_f32 v[56:57], v[56:57], v[176:177] op_sel_hi:[1,0]
	v_pk_mul_f32 v[50:51], v[50:51], v[176:177] op_sel_hi:[1,0]
	v_pk_mul_f32 v[52:53], v[52:53], v[176:177] op_sel_hi:[1,0]
	v_pk_mul_f32 v[118:119], v[118:119], v[176:177] op_sel_hi:[1,0]
	v_pk_mul_f32 v[120:121], v[120:121], v[176:177] op_sel_hi:[1,0]
	v_pk_mul_f32 v[114:115], v[114:115], v[176:177] op_sel_hi:[1,0]
	v_pk_mul_f32 v[116:117], v[116:117], v[176:177] op_sel_hi:[1,0]
	v_cvt_pk_bf16_f32 v234, v54, v55
	v_cvt_pk_bf16_f32 v235, v56, v57
	v_cvt_pk_bf16_f32 v236, v50, v51
	v_cvt_pk_bf16_f32 v237, v52, v53
	v_cvt_pk_bf16_f32 v238, v118, v119
	v_cvt_pk_bf16_f32 v239, v120, v121
	v_cvt_pk_bf16_f32 v240, v114, v115
	v_cvt_pk_bf16_f32 v241, v116, v117
	global_store_dwordx4 v[220:221], v[234:237], off
	global_store_dwordx4 v[220:221], v[238:241], off offset:256
	v_add_u32_e32 v224, 0x20, v144
	v_lshlrev_b64 v[222:223], s57, v[224:225]
	v_lshl_add_u64 v[220:221], v[222:223], 1, v[146:147]
	v_pk_mul_f32 v[46:47], v[46:47], v[180:181] op_sel_hi:[1,0]
	v_pk_mul_f32 v[48:49], v[48:49], v[180:181] op_sel_hi:[1,0]
	v_pk_mul_f32 v[42:43], v[42:43], v[180:181] op_sel_hi:[1,0]
	v_pk_mul_f32 v[44:45], v[44:45], v[180:181] op_sel_hi:[1,0]
	v_pk_mul_f32 v[110:111], v[110:111], v[180:181] op_sel_hi:[1,0]
	v_pk_mul_f32 v[112:113], v[112:113], v[180:181] op_sel_hi:[1,0]
	v_pk_mul_f32 v[106:107], v[106:107], v[180:181] op_sel_hi:[1,0]
	v_pk_mul_f32 v[108:109], v[108:109], v[180:181] op_sel_hi:[1,0]
	v_cvt_pk_bf16_f32 v226, v46, v47
	v_cvt_pk_bf16_f32 v227, v48, v49
	v_cvt_pk_bf16_f32 v228, v42, v43
	v_cvt_pk_bf16_f32 v229, v44, v45
	v_cvt_pk_bf16_f32 v230, v110, v111
	v_cvt_pk_bf16_f32 v231, v112, v113
	v_cvt_pk_bf16_f32 v232, v106, v107
	v_cvt_pk_bf16_f32 v233, v108, v109
	global_store_dwordx4 v[220:221], v[226:229], off
	global_store_dwordx4 v[220:221], v[230:233], off offset:256
	v_add_u32_e32 v224, 0x30, v144
	v_lshlrev_b64 v[222:223], s57, v[224:225]
	v_lshl_add_u64 v[220:221], v[222:223], 1, v[146:147]
	v_pk_mul_f32 v[38:39], v[38:39], v[184:185] op_sel_hi:[1,0]
	v_pk_mul_f32 v[40:41], v[40:41], v[184:185] op_sel_hi:[1,0]
	v_pk_mul_f32 v[34:35], v[34:35], v[184:185] op_sel_hi:[1,0]
	v_pk_mul_f32 v[36:37], v[36:37], v[184:185] op_sel_hi:[1,0]
	v_pk_mul_f32 v[102:103], v[102:103], v[184:185] op_sel_hi:[1,0]
	v_pk_mul_f32 v[104:105], v[104:105], v[184:185] op_sel_hi:[1,0]
	v_pk_mul_f32 v[98:99], v[98:99], v[184:185] op_sel_hi:[1,0]
	v_pk_mul_f32 v[100:101], v[100:101], v[184:185] op_sel_hi:[1,0]
	v_cvt_pk_bf16_f32 v234, v38, v39
	v_cvt_pk_bf16_f32 v235, v40, v41
	v_cvt_pk_bf16_f32 v236, v34, v35
	v_cvt_pk_bf16_f32 v237, v36, v37
	v_cvt_pk_bf16_f32 v238, v102, v103
	v_cvt_pk_bf16_f32 v239, v104, v105
	v_cvt_pk_bf16_f32 v240, v98, v99
	v_cvt_pk_bf16_f32 v241, v100, v101
	global_store_dwordx4 v[220:221], v[234:237], off
	global_store_dwordx4 v[220:221], v[238:241], off offset:256
	v_add_u32_e32 v224, 0x80, v144
	v_lshlrev_b64 v[222:223], s57, v[224:225]
	v_lshl_add_u64 v[220:221], v[222:223], 1, v[146:147]
	v_pk_mul_f32 v[30:31], v[30:31], v[188:189] op_sel_hi:[1,0]
	v_pk_mul_f32 v[32:33], v[32:33], v[188:189] op_sel_hi:[1,0]
	v_pk_mul_f32 v[26:27], v[26:27], v[188:189] op_sel_hi:[1,0]
	v_pk_mul_f32 v[28:29], v[28:29], v[188:189] op_sel_hi:[1,0]
	v_pk_mul_f32 v[94:95], v[94:95], v[188:189] op_sel_hi:[1,0]
	v_pk_mul_f32 v[96:97], v[96:97], v[188:189] op_sel_hi:[1,0]
; __device__ __forceinline__ unsigned cvt_pk_bf16(float lo, float hi) { f32x2_cv v = {lo, hi}; bf16x2_cv b = __builtin_convertvector(v, bf16x2_cv); return __builtin_bit_cast(unsigned, b); }
;     __device__ __forceinline__ void operator()(const f32x4 (&acc)[2][2][4][2], const Unit& u, int wr, int wc, int fr, int fq) const {
;     ...
; #pragma unroll
;         for (int ai = 0; ai < 2; ++ai)
; #pragma unroll
;             for (int m = 0; m < 4; ++m) {
;                 const int row = row0 + ai * HALF + m * 16; const float rs = row_rstd(rsp, row, fq) * sc;
;                 bf16_t* rowp = base + (size_t)row * ldc + colt;
; #pragma unroll
;                 for (int bj = 0; bj < 2; ++bj) {
;                     const f32x4 v0 = acc[ai][bj][m][0] * rs, v1 = acc[ai][bj][m][1] * rs;
;                     u32x4 w; w.x = cvt_pk_bf16(v0[0], v0[1]); w.y = cvt_pk_bf16(v0[2], v0[3]); w.z = cvt_pk_bf16(v1[0], v1[1]); w.w = cvt_pk_bf16(v1[2], v1[3]);
;                     *(u32x4*)(rowp + bj * HALF) = w;
;                 }
;             }
	v_pk_mul_f32 v[90:91], v[90:91], v[188:189] op_sel_hi:[1,0]
	v_pk_mul_f32 v[92:93], v[92:93], v[188:189] op_sel_hi:[1,0]
	v_cvt_pk_bf16_f32 v226, v30, v31
	v_cvt_pk_bf16_f32 v227, v32, v33
	v_cvt_pk_bf16_f32 v228, v26, v27
	v_cvt_pk_bf16_f32 v229, v28, v29
	v_cvt_pk_bf16_f32 v230, v94, v95
	v_cvt_pk_bf16_f32 v231, v96, v97
	v_cvt_pk_bf16_f32 v232, v90, v91
	v_cvt_pk_bf16_f32 v233, v92, v93
	global_store_dwordx4 v[220:221], v[226:229], off
	global_store_dwordx4 v[220:221], v[230:233], off offset:256
	v_add_u32_e32 v224, 0x90, v144
	v_lshlrev_b64 v[222:223], s57, v[224:225]
	v_lshl_add_u64 v[220:221], v[222:223], 1, v[146:147]
	v_pk_mul_f32 v[22:23], v[22:23], v[192:193] op_sel_hi:[1,0]
	v_pk_mul_f32 v[24:25], v[24:25], v[192:193] op_sel_hi:[1,0]
	v_pk_mul_f32 v[18:19], v[18:19], v[192:193] op_sel_hi:[1,0]
	v_pk_mul_f32 v[20:21], v[20:21], v[192:193] op_sel_hi:[1,0]
	v_pk_mul_f32 v[86:87], v[86:87], v[192:193] op_sel_hi:[1,0]
	v_pk_mul_f32 v[88:89], v[88:89], v[192:193] op_sel_hi:[1,0]
	v_pk_mul_f32 v[82:83], v[82:83], v[192:193] op_sel_hi:[1,0]
	v_pk_mul_f32 v[84:85], v[84:85], v[192:193] op_sel_hi:[1,0]
	v_cvt_pk_bf16_f32 v234, v22, v23
	v_cvt_pk_bf16_f32 v235, v24, v25
	v_cvt_pk_bf16_f32 v236, v18, v19
	v_cvt_pk_bf16_f32 v237, v20, v21
	v_cvt_pk_bf16_f32 v238, v86, v87
	v_cvt_pk_bf16_f32 v239, v88, v89
	v_cvt_pk_bf16_f32 v240, v82, v83
	v_cvt_pk_bf16_f32 v241, v84, v85
	global_store_dwordx4 v[220:221], v[234:237], off
	global_store_dwordx4 v[220:221], v[238:241], off offset:256
	v_add_u32_e32 v224, 0xa0, v144
	v_lshlrev_b64 v[222:223], s57, v[224:225]
	v_lshl_add_u64 v[220:221], v[222:223], 1, v[146:147]
	v_pk_mul_f32 v[14:15], v[14:15], v[196:197] op_sel_hi:[1,0]
	v_pk_mul_f32 v[16:17], v[16:17], v[196:197] op_sel_hi:[1,0]
	v_pk_mul_f32 v[10:11], v[10:11], v[196:197] op_sel_hi:[1,0]
	v_pk_mul_f32 v[12:13], v[12:13], v[196:197] op_sel_hi:[1,0]
	v_pk_mul_f32 v[78:79], v[78:79], v[196:197] op_sel_hi:[1,0]
	v_pk_mul_f32 v[80:81], v[80:81], v[196:197] op_sel_hi:[1,0]
	v_pk_mul_f32 v[74:75], v[74:75], v[196:197] op_sel_hi:[1,0]
	v_pk_mul_f32 v[76:77], v[76:77], v[196:197] op_sel_hi:[1,0]
	v_cvt_pk_bf16_f32 v226, v14, v15
	v_cvt_pk_bf16_f32 v227, v16, v17
	v_cvt_pk_bf16_f32 v228, v10, v11
	v_cvt_pk_bf16_f32 v229, v12, v13
	v_cvt_pk_bf16_f32 v230, v78, v79
	v_cvt_pk_bf16_f32 v231, v80, v81
	v_cvt_pk_bf16_f32 v232, v74, v75
	v_cvt_pk_bf16_f32 v233, v76, v77
	global_store_dwordx4 v[220:221], v[226:229], off
	global_store_dwordx4 v[220:221], v[230:233], off offset:256
	v_add_u32_e32 v224, 0xb0, v144
	v_lshlrev_b64 v[222:223], s57, v[224:225]
	v_lshl_add_u64 v[220:221], v[222:223], 1, v[146:147]
	v_pk_mul_f32 v[6:7], v[6:7], v[214:215] op_sel_hi:[1,0]
	v_pk_mul_f32 v[8:9], v[8:9], v[214:215] op_sel_hi:[1,0]
	v_pk_mul_f32 v[2:3], v[2:3], v[214:215] op_sel_hi:[1,0]
	v_pk_mul_f32 v[4:5], v[4:5], v[214:215] op_sel_hi:[1,0]
	v_pk_mul_f32 v[70:71], v[70:71], v[214:215] op_sel_hi:[1,0]
	v_pk_mul_f32 v[72:73], v[72:73], v[214:215] op_sel_hi:[1,0]
	v_pk_mul_f32 v[66:67], v[66:67], v[214:215] op_sel_hi:[1,0]
	v_pk_mul_f32 v[68:69], v[68:69], v[214:215] op_sel_hi:[1,0]
	v_cvt_pk_bf16_f32 v234, v6, v7
	v_cvt_pk_bf16_f32 v235, v8, v9
	v_cvt_pk_bf16_f32 v236, v2, v3
	v_cvt_pk_bf16_f32 v237, v4, v5
	v_cvt_pk_bf16_f32 v238, v70, v71
	v_cvt_pk_bf16_f32 v239, v72, v73
	v_cvt_pk_bf16_f32 v240, v66, v67
	v_cvt_pk_bf16_f32 v241, v68, v69
	global_store_dwordx4 v[220:221], v[234:237], off
	global_store_dwordx4 v[220:221], v[238:241], off offset:256
	s_branch .LBB0_335
.Lsplit_dt_align:
	s_and_b64 vcc, exec, s[14:15]
	s_cbranch_vccz .LBB0_335
	s_barrier
